# retention: distance-2 global prefetch (second register set copied per chunk, counted vmcnt per role) + state-update moved ahead + b64 state publish
# speedup vs baseline: 1.0192x; 1.0072x over previous
; #define LAS __attribute__((address_space(3)))
; __device__ __forceinline__ int lane_id_asm() { int l; asm volatile("v_mbcnt_lo_u32_b32 %0, -1, 0\n\tv_mbcnt_hi_u32_b32 %0, -1, %0" : "=v"(l)); return l; }
; __device__ __forceinline__ void ret_mfma(const Params& P, LAS unsigned char* lds, int wave) {
;     ...
;     const int lane = lane_id_asm(), t = wave * 64 + lane, q32 = lane & 31, hf = lane >> 5, i16 = lane & 15, blk = (lane >> 4) & 1;
;     const int trrow = 8 * hf + (i16 >> 2), trcol = (16 * blk + 4 * (i16 & 3)) * 2;
;     for (int unit = blockIdx.x; unit < 256; unit += gridDim.x) {
;         const int xcd_ = unit & 7, idx_ = unit >> 3, bh = xcd_ * 4 + (idx_ >> 3), slice = idx_ & 7, b = bh >> 2, hh = bh & 3;
;         const float gam = 1.f - exp2f(-5.f - (float)hh), lg = log2f(gam), g64 = exp2f(lg * 64.f);
;         for (int i = t; i < 33792 / 16; i += NTHREADS) *(LAS u32x4*)(lds + ST_OFF + i * 16) = (u32x4){0u, 0u, 0u, 0u};
;         f32x16 st[2];
; #pragma unroll
;         for (int a = 0; a < 2; ++a)
; #pragma unroll
;             for (int i = 0; i < 16; ++i) st[a][i] = 0.f;
;         const size_t rb = (size_t)b * SEQ;
;         float dec[16];
;         { const int mblk = (wave & 3) >> 1, nblk = wave & 1, n = nblk * 32 + q32;
; #pragma unroll
;           for (int i = 0; i < 16; ++i) { const int mm = mblk * 32 + 8 * (i >> 2) + 4 * hf + (i & 3); const int dist = n > mm ? n - mm : mm - n;
;               dec[i] = wave < 4 ? __builtin_amdgcn_exp2f(lg * (float)(dist - (63 - mm))) : __builtin_amdgcn_exp2f(lg * (float)(n + 1)); } }
;         u32x4 pq[4], pkk[4], pvv;
;         const int vr = t >> 3, vc = t & 7;
.LBB0_246:
	s_or_b64 exec, exec, s[50:51]
	s_add_u32 s60, s54, 0x1f000000
	s_addc_u32 s61, s55, 0
	s_cmpk_gt_i32 s2, 0xff
	s_waitcnt lgkmcnt(0)
	s_barrier
	v_mbcnt_lo_u32_b32 v0, -1, 0
	v_mbcnt_hi_u32_b32 v0, -1, v0
	s_cbranch_scc1 .LBB0_270
	v_ashrrev_i32_e32 v3, 5, v0
	v_and_b32_e32 v8, 31, v0
	v_readlane_b32 s4, v254, 4
	s_cmpk_lt_u32 s3, 0x100
	v_lshlrev_b32_e32 v5, 3, v3
	v_lshrrev_b32_e32 v2, 2, v0
	v_and_or_b32 v84, s4, 32, v8
	s_cselect_b64 s[4:5], -1, 0
	s_cmpk_gt_u32 s3, 0xff
	v_add_u32_e32 v1, s64, v0
	v_and_or_b32 v6, v2, 3, v5
	v_lshlrev_b32_e32 v2, 2, v0
	v_and_b32_e32 v4, 16, v0
	s_cselect_b64 s[10:11], -1, 0
	s_lshl_b32 s6, s33, 4
	v_and_or_b32 v2, v2, 12, v4
	s_and_b32 s6, s6, 32
	v_lshlrev_b32_e32 v86, 2, v3
	v_ashrrev_i32_e32 v88, 3, v1
	s_movk_i32 s9, 0xc0
	v_lshlrev_b32_e32 v7, 1, v2
	v_add_u32_e32 v9, s6, v86
	v_mul_lo_u32 v13, v88, s9
	s_add_i32 s6, 0, 0x10800
	v_add_u32_e32 v13, s6, v13
	v_add_u32_e32 v148, s6, v7
	s_add_i32 s6, s64, 0
	s_add_i32 s16, 0, 0x16800
	s_add_i32 s7, 0, 0x1ec00
	v_add_u32_e32 v7, s6, v7
	s_add_i32 s6, s16, s64
	v_lshlrev_b32_e32 v149, 4, v3
	v_mul_u32_u24_e32 v15, 0x210, v84
	v_lshl_add_u32 v14, v8, 1, s6
	v_add3_u32 v150, 0, v15, v149
	s_movk_i32 s6, 0x90
	v_mov_b32_e32 v15, s7
	v_add_u32_e32 v2, 1, v84
	v_mad_u32_u24 v151, v84, s6, v15
	s_add_i32 s6, s33, -4
	v_cvt_f32_ubyte0_e32 v85, v2
	v_and_b32_e32 v10, 7, v0
	v_lshlrev_b32_e32 v2, 3, v0
	v_lshlrev_b32_e32 v11, 4, v0
	s_lshr_b32 s14, s6, 1
	v_cmp_lt_u32_e64 s[6:7], 31, v0
	v_sub_u32_e32 v0, v84, v9
	v_sub_u32_e32 v16, 0, v0
	v_max_i32_e32 v16, v0, v16
	s_movk_i32 s21, 0xffc1
	v_add3_u32 v16, v9, v16, s21
	v_cvt_f32_i32_e32 v152, v16
	v_xad_u32 v16, v9, -1, v84
	v_sub_u32_e32 v17, 0, v16
	v_max_i32_e32 v16, v16, v17
	s_movk_i32 s21, 0xffc2
	v_add3_u32 v16, v9, v16, s21
	v_cvt_f32_i32_e32 v153, v16
	v_add_u32_e32 v16, -2, v0
	v_sub_u32_e32 v17, 2, v0
	v_max_i32_e32 v16, v16, v17
	s_movk_i32 s21, 0xffc3
	v_add3_u32 v16, v9, v16, s21
	v_cvt_f32_i32_e32 v154, v16
	v_add_u32_e32 v16, -3, v0
	v_sub_u32_e32 v17, 3, v0
	v_max_i32_e32 v16, v16, v17
	s_movk_i32 s21, 0xffc4
	v_add3_u32 v16, v9, v16, s21
	v_cvt_f32_i32_e32 v155, v16
	v_add_u32_e32 v16, -8, v0
	v_sub_u32_e32 v17, 8, v0
	v_max_i32_e32 v16, v16, v17
	s_movk_i32 s21, 0xffc9
	v_add3_u32 v16, v9, v16, s21
	v_cvt_f32_i32_e32 v156, v16
	v_add_u32_e32 v16, -9, v0
	v_sub_u32_e32 v17, 9, v0
	v_max_i32_e32 v16, v16, v17
	s_movk_i32 s21, 0xffca
	v_add3_u32 v16, v9, v16, s21
	v_cvt_f32_i32_e32 v157, v16
	v_add_u32_e32 v16, -10, v0
	v_sub_u32_e32 v17, 10, v0
	v_max_i32_e32 v16, v16, v17
	s_movk_i32 s21, 0xffcb
	v_add3_u32 v16, v9, v16, s21
	v_cvt_f32_i32_e32 v158, v16
	v_add_u32_e32 v16, -11, v0
	v_sub_u32_e32 v17, 11, v0
	v_max_i32_e32 v16, v16, v17
	s_movk_i32 s21, 0xffcc
	v_add3_u32 v16, v9, v16, s21
	v_cvt_f32_i32_e32 v159, v16
	v_add_u32_e32 v16, -16, v0
	v_sub_u32_e32 v17, 16, v0
	v_max_i32_e32 v16, v16, v17
	s_movk_i32 s21, 0xffd1
	v_add3_u32 v16, v9, v16, s21
	v_cvt_f32_i32_e32 v160, v16
	v_subrev_u32_e32 v16, 17, v0
	v_sub_u32_e32 v17, 17, v0
	v_max_i32_e32 v16, v16, v17
	s_movk_i32 s21, 0xffd2
	v_add3_u32 v16, v9, v16, s21
	v_cvt_f32_i32_e32 v161, v16
	v_subrev_u32_e32 v16, 18, v0
	v_sub_u32_e32 v17, 18, v0
	v_max_i32_e32 v16, v16, v17
	s_movk_i32 s21, 0xffd3
	v_add3_u32 v16, v9, v16, s21
	v_cvt_f32_i32_e32 v162, v16
	v_subrev_u32_e32 v16, 19, v0
	v_sub_u32_e32 v17, 19, v0
	v_max_i32_e32 v16, v16, v17
	s_movk_i32 s21, 0xffd4
	v_add3_u32 v16, v9, v16, s21
	v_cvt_f32_i32_e32 v163, v16
	v_subrev_u32_e32 v16, 24, v0
	v_sub_u32_e32 v17, 24, v0
	v_max_i32_e32 v16, v16, v17
	s_movk_i32 s21, 0xffd9
	v_add3_u32 v16, v9, v16, s21
	v_cvt_f32_i32_e32 v164, v16
	v_subrev_u32_e32 v16, 25, v0
	v_sub_u32_e32 v17, 25, v0
	v_max_i32_e32 v16, v16, v17
	s_movk_i32 s21, 0xffda
	v_add3_u32 v16, v9, v16, s21
	v_cvt_f32_i32_e32 v165, v16
	v_subrev_u32_e32 v16, 26, v0
	v_sub_u32_e32 v17, 26, v0
	v_max_i32_e32 v16, v16, v17
	s_movk_i32 s21, 0xffdb
	v_add3_u32 v16, v9, v16, s21
	v_cvt_f32_i32_e32 v166, v16
	v_subrev_u32_e32 v16, 27, v0
	v_sub_u32_e32 v0, 27, v0
	v_max_i32_e32 v0, v16, v0
	s_movk_i32 s21, 0xffdc
	v_add3_u32 v0, v9, v0, s21
	s_movk_i32 s8, 0x840
	s_lshr_b32 s18, s3, 7
	v_cvt_f32_i32_e32 v167, v0
	v_add_u32_e32 v0, 0x200, v1
	v_cmp_gt_i32_e64 s[0:1], s8, v1
	v_ashrrev_i32_e32 v94, 5, v0
	v_add_u32_e32 v0, 0x400, v1
	v_mul_lo_u32 v3, v3, s8
	s_mul_i32 s8, s18, 0x4200
	s_movk_i32 s17, 0x210
	v_ashrrev_i32_e32 v92, 5, v1
	v_ashrrev_i32_e32 v96, 5, v0
	v_add_u32_e32 v0, 0x600, v1
	v_add_u32_e32 v169, 0xfffffe00, v1
	v_mov_b32_e32 v1, s8
	v_and_b32_e32 v2, 0xf8, v2
	v_and_b32_e32 v12, 0x1f0, v11
	v_ashrrev_i32_e32 v98, 5, v0
	v_mad_u32_u24 v1, v8, s17, v1
	s_mov_b32 s15, 0
	v_mov_b32_e32 v91, 0
	v_lshlrev_b32_e32 v4, 3, v10
	v_add_u32_e32 v12, 0, v12
	v_lshlrev_b32_e32 v10, 4, v10
	s_lshl_b32 s19, s18, 6
	v_add_u32_e32 v5, v151, v5
	v_lshl_add_u32 v15, s14, 6, v148
	s_lshl_b32 s20, s14, 5
	v_mul_lo_u32 v0, v92, s17
	v_mul_lo_u32 v9, v94, s17
	v_mul_lo_u32 v16, v96, s17
	v_mul_lo_u32 v17, v98, s17
	v_mul_lo_u32 v168, v6, s9
	v_mul_lo_u32 v6, v6, s17
	v_lshlrev_b32_e32 v90, 1, v2
	s_add_i32 s16, s16, s68
	v_add3_u32 v1, v1, v149, 0
	v_ashrrev_i32_e32 v89, 31, v88
	v_ashrrev_i32_e32 v87, 31, v86
	v_ashrrev_i32_e32 v93, 31, v92
	v_ashrrev_i32_e32 v95, 31, v94
	v_ashrrev_i32_e32 v97, 31, v96
	v_ashrrev_i32_e32 v99, 31, v98
	v_lshl_add_u64 v[100:101], s[44:45], 0, v[90:91]
	v_add_u32_e32 v170, s16, v11
	v_add_u32_e32 v171, 0xe400, v1
	v_add_u32_e32 v172, 0x8400, v1
	s_movk_i32 s24, 0x63f
	s_mov_b32 s25, 0xc2fc0000
	s_mov_b32 s26, 0x800000
	v_lshlrev_b32_e32 v90, 1, v2
	v_lshlrev_b32_e32 v102, 1, v4
	s_lshl_b64 s[16:17], s[14:15], 2
	s_lshl_b32 s27, s20, 1
	v_add_u32_e32 v173, v12, v0
	v_add_u32_e32 v174, v12, v9
	v_add_u32_e32 v175, v12, v16
	v_add_u32_e32 v176, v12, v17
	v_add_u32_e32 v177, v13, v10
	v_add_u32_e32 v178, s19, v5
	v_add_u32_e32 v179, v7, v6
	v_add_u32_e32 v180, v14, v3
	v_add_u32_e32 v181, v15, v168
	v_mov_b32_e32 v186, v91
	v_mov_b32_e32 v187, v91
	v_mov_b32_e32 v188, v91
	v_mov_b32_e32 v189, v91
	v_mov_b32_e32 v182, 0x42800000
	v_mov_b32_e32 v183, 0x42000000
	v_mbcnt_hi_u32_b32 v184, -1, v244
	v_and_b32_e32 v242, 31, v184
	v_mul_u32_u24_e32 v242, 0x210, v242
	v_lshrrev_b32_e32 v103, 5, v184
	v_lshl_add_u32 v242, v103, 3, v242
	v_add_u32_e32 v242, s64, v242
	v_add_u32_e32 v242, 0x16800, v242
	s_mov_b32 s28, s2
	s_branch .LBB0_249

; #define LAS __attribute__((address_space(3)))
; __device__ __forceinline__ void ret_mfma(const Params& P, LAS unsigned char* lds, int wave) {
;     ...
;         const int xcd_ = unit & 7, idx_ = unit >> 3, bh = xcd_ * 4 + (idx_ >> 3), slice = idx_ & 7, b = bh >> 2, hh = bh & 3;
;         const float gam = 1.f - exp2f(-5.f - (float)hh), lg = log2f(gam), g64 = exp2f(lg * 64.f);
;         for (int i = t; i < 33792 / 16; i += NTHREADS) *(LAS u32x4*)(lds + ST_OFF + i * 16) = (u32x4){0u, 0u, 0u, 0u};
;         f32x16 st[2];
; #pragma unroll
;         for (int a = 0; a < 2; ++a)
; #pragma unroll
;             for (int i = 0; i < 16; ++i) st[a][i] = 0.f;
;         const size_t rb = (size_t)b * SEQ;
;         float dec[16];
;         { const int mblk = (wave & 3) >> 1, nblk = wave & 1, n = nblk * 32 + q32;
; #pragma unroll
;           for (int i = 0; i < 16; ++i) { const int mm = mblk * 32 + 8 * (i >> 2) + 4 * hf + (i & 3); const int dist = n > mm ? n - mm : mm - n;
;               dec[i] = wave < 4 ? __builtin_amdgcn_exp2f(lg * (float)(dist - (63 - mm))) : __builtin_amdgcn_exp2f(lg * (float)(n + 1)); } }
;         u32x4 pq[4], pkk[4], pvv;
;         const int vr = t >> 3, vc = t & 7;
; #pragma unroll
;         for (int i = 0; i < 4; ++i) { const int id = t + 512 * i, r = id >> 5, ch = id & 31;
;             pq[i] = *(const u32x4*)(QK + (rb + r) * 2048 + hh * 256 + ch * 8); pkk[i] = *(const u32x4*)(QK + (rb + r) * 2048 + 1024 + hh * 256 + ch * 8); }
;         pvv = *(const u32x4*)(V + (rb + vr) * 2048 + hh * 512 + slice * 64 + vc * 8);
.LBB0_252:
	s_or_b64 exec, exec, s[8:9]
	s_ashr_i32 s9, s28, 6
	s_and_b32 s23, s9, 3
	v_cvt_f32_ubyte0_e32 v0, s23
	v_sub_f32_e32 v0, 0xc0a00000, v0
	v_cmp_gt_f32_e32 vcc, s25, v0
	s_lshl_b32 s8, s28, 2
	s_and_b32 s8, s8, 28
	v_cndmask_b32_e32 v1, 0, v182, vcc
	v_add_f32_e32 v0, v0, v1
	s_add_i32 s8, s8, s9
	v_exp_f32_e32 v0, v0
	s_bfe_u32 s22, s28, 0x30003
	s_ashr_i32 s8, s8, 2
	s_and_b64 s[18:19], vcc, exec
	s_cselect_b32 s9, 0xffffffc0, 0
	v_ldexp_f32 v0, v0, s9
	v_sub_f32_e32 v0, 1.0, v0
	v_cmp_gt_f32_e32 vcc, s26, v0
	s_and_b64 s[18:19], vcc, exec
	s_cselect_b32 s9, 32, 0
	v_ldexp_f32 v0, v0, s9
	v_log_f32_e32 v2, v0
	v_cndmask_b32_e32 v1, 0, v183, vcc
	s_mov_b32 s21, s15
	v_mov_b32_e32 v103, v91
	v_sub_f32_e32 v1, v2, v1
	v_mul_f32_e32 v2, 0x42800000, v1
	v_cmp_gt_f32_e32 vcc, s25, v2
	s_and_b64 s[18:19], vcc, exec
	s_cselect_b32 s9, 0xffffffc0, 0
	v_cndmask_b32_e32 v2, 0, v182, vcc
	v_fmac_f32_e32 v2, 0x42800000, v1
	v_exp_f32_e32 v2, v2
	v_mul_f32_e32 v3, v1, v85
	v_mul_f32_e32 v4, v1, v152
	v_exp_f32_e32 v3, v3
	v_ldexp_f32 v106, v2, s9
	v_mul_f32_e32 v2, v1, v153
	v_exp_f32_e32 v105, v2
	v_mul_f32_e32 v2, v1, v154
	v_exp_f32_e32 v110, v2
	v_mul_f32_e32 v2, v1, v155
	v_exp_f32_e32 v111, v2
	v_mul_f32_e32 v2, v1, v156
	v_exp_f32_e32 v104, v4
	v_exp_f32_e32 v112, v2
	v_mul_f32_e32 v2, v1, v157
	v_exp_f32_e32 v113, v2
	v_mul_f32_e32 v2, v1, v158
	s_ashr_i32 s9, s8, 31
	v_exp_f32_e32 v114, v2
	v_mul_f32_e32 v2, v1, v159
	v_exp_f32_e32 v115, v2
	v_mul_f32_e32 v2, v1, v160
	s_lshl_b64 s[18:19], s[8:9], 12
	v_cndmask_b32_e64 v108, v3, v104, s[4:5]
	v_exp_f32_e32 v116, v2
	v_lshl_add_u64 v[2:3], s[18:19], 0, v[92:93]
	v_lshlrev_b64 v[2:3], 12, v[2:3]
	v_lshl_add_u64 v[2:3], s[44:45], 0, v[2:3]
	s_lshl_b32 s14, s23, 9
	v_lshl_add_u64 v[2:3], v[2:3], 0, s[14:15]
	v_lshl_add_u64 v[2:3], v[2:3], 0, v[90:91]
	s_waitcnt vmcnt(0)
	flat_load_dwordx4 v[48:51], v[2:3]
	flat_load_dwordx4 v[52:55], v[2:3] offset:2048
	v_lshl_add_u64 v[2:3], s[18:19], 0, v[94:95]
	v_lshlrev_b64 v[2:3], 12, v[2:3]
	v_lshl_add_u64 v[2:3], s[44:45], 0, v[2:3]
	v_lshl_add_u64 v[2:3], v[2:3], 0, s[14:15]
	v_lshl_add_u64 v[2:3], v[2:3], 0, v[90:91]
	flat_load_dwordx4 v[56:59], v[2:3]
	flat_load_dwordx4 v[60:63], v[2:3] offset:2048
	v_lshl_add_u64 v[2:3], s[18:19], 0, v[96:97]
	v_lshlrev_b64 v[2:3], 12, v[2:3]
	v_lshl_add_u64 v[2:3], s[44:45], 0, v[2:3]
	v_lshl_add_u64 v[2:3], v[2:3], 0, s[14:15]
	v_lshl_add_u64 v[2:3], v[2:3], 0, v[90:91]
	flat_load_dwordx4 v[64:67], v[2:3]
	flat_load_dwordx4 v[68:71], v[2:3] offset:2048
	v_lshl_add_u64 v[2:3], s[18:19], 0, v[98:99]
	v_lshlrev_b64 v[2:3], 12, v[2:3]
	v_lshl_add_u64 v[2:3], s[44:45], 0, v[2:3]
	v_lshl_add_u64 v[2:3], v[2:3], 0, s[14:15]
	v_lshl_add_u64 v[2:3], v[2:3], 0, v[90:91]
	flat_load_dwordx4 v[72:75], v[2:3]
	flat_load_dwordx4 v[76:79], v[2:3] offset:2048
	v_lshl_add_u64 v[2:3], s[18:19], 0, v[88:89]
	v_lshlrev_b64 v[2:3], 12, v[2:3]
	v_lshl_add_u64 v[2:3], s[36:37], 0, v[2:3]
	s_lshl_b32 s8, s23, 10
	s_mov_b32 s9, s15
	v_lshl_add_u64 v[2:3], v[2:3], 0, s[8:9]
	s_lshl_b32 s20, s22, 7
	v_lshl_add_u64 v[2:3], v[2:3], 0, s[20:21]
	v_lshl_add_u64 v[2:3], v[2:3], 0, v[102:103]
	flat_load_dwordx4 v[80:83], v[2:3]
	s_add_u32 s8, s36, s8
	s_addc_u32 s9, s37, 0
	s_add_u32 s8, s8, s20
	v_mul_f32_e32 v2, v1, v161
	s_addc_u32 s9, s9, 0
	s_lshl_b32 s20, s23, 6
	v_exp_f32_e32 v117, v2
	v_mul_f32_e32 v2, v1, v162
	s_add_u32 s20, s60, s20
	v_exp_f32_e32 v118, v2
	v_mul_f32_e32 v2, v1, v163
	s_addc_u32 s21, s61, 0
	s_lshl_b32 s22, s22, 3
	v_exp_f32_e32 v119, v2
	v_mul_f32_e32 v2, v1, v164
	s_add_u32 s20, s20, s22
	v_exp_f32_e32 v120, v2
	v_mul_f32_e32 v2, v1, v165
	s_addc_u32 s21, s21, 0
	v_exp_f32_e32 v121, v2
	v_mul_f32_e32 v2, v1, v166
	v_mul_f32_e32 v1, v1, v167
	s_add_u32 s20, s20, s16
	v_exp_f32_e32 v122, v2
	v_exp_f32_e32 v123, v1
	s_addc_u32 s21, s21, s17
	v_lshl_add_u64 v[124:125], s[8:9], 0, v[102:103]
	s_add_u32 s8, s8, s27
	v_mov_b32_e32 v0, 0
	s_addc_u32 s9, s9, 0
	s_mov_b32 s29, 0
	v_mov_b32_e32 v126, v106
	v_mov_b32_e32 v127, v106
	v_lshl_add_u64 v[128:129], v[86:87], 1, s[8:9]
	v_mov_b32_e32 v109, v108
	v_lshl_add_u64 v[144:145], v[100:101], 0, s[14:15]
	v_mov_b32_e32 v1, v0
	v_mov_b32_e32 v2, v0
	v_mov_b32_e32 v3, v0
	v_mov_b32_e32 v4, v0
	v_mov_b32_e32 v5, v0
	v_mov_b32_e32 v6, v0
	v_mov_b32_e32 v7, v0
	v_mov_b32_e32 v8, v0
	v_mov_b32_e32 v9, v0
	v_mov_b32_e32 v10, v0
	v_mov_b32_e32 v11, v0
	v_mov_b32_e32 v12, v0
	v_mov_b32_e32 v13, v0
	v_mov_b32_e32 v14, v0
	v_mov_b32_e32 v15, v0
	v_mov_b32_e32 v16, v0
	v_mov_b32_e32 v17, v0
	v_mov_b32_e32 v18, v0
	v_mov_b32_e32 v19, v0
	v_mov_b32_e32 v20, v0
	v_mov_b32_e32 v21, v0
	v_mov_b32_e32 v22, v0
	v_mov_b32_e32 v23, v0
	v_mov_b32_e32 v24, v0
	v_mov_b32_e32 v25, v0
	v_mov_b32_e32 v26, v0
	v_mov_b32_e32 v27, v0
	v_mov_b32_e32 v28, v0
	v_mov_b32_e32 v29, v0
	v_mov_b32_e32 v30, v0
	v_mov_b32_e32 v31, v0
	s_add_u32 s8, s18, 64
	s_addc_u32 s9, s19, 0
	v_lshl_add_u64 v[32:33], s[8:9], 0, v[92:93]
	v_lshlrev_b64 v[32:33], 12, v[32:33]
	v_lshl_add_u64 v[32:33], v[144:145], 0, v[32:33]
	global_load_dwordx4 v[226:229], v[32:33], off
	global_load_dwordx4 v[230:233], v[32:33], off offset:2048
	v_lshl_add_u64 v[32:33], s[8:9], 0, v[94:95]
	v_lshlrev_b64 v[32:33], 12, v[32:33]
	v_lshl_add_u64 v[32:33], v[144:145], 0, v[32:33]
	global_load_dwordx4 v[234:237], v[32:33], off
	global_load_dwordx4 v[238:241], v[32:33], off offset:2048
	v_lshl_add_u64 v[32:33], s[8:9], 0, v[96:97]
	v_lshlrev_b64 v[32:33], 12, v[32:33]
	v_lshl_add_u64 v[32:33], v[144:145], 0, v[32:33]
	global_load_dwordx4 v[246:249], v[32:33], off
	global_load_dwordx4 v[250:253], v[32:33], off offset:2048
	v_lshl_add_u64 v[32:33], s[8:9], 0, v[98:99]
	v_lshlrev_b64 v[32:33], 12, v[32:33]
	v_lshl_add_u64 v[32:33], v[144:145], 0, v[32:33]
	global_load_dwordx4 v[206:209], v[32:33], off
	global_load_dwordx4 v[130:133], v[32:33], off offset:2048
	v_lshl_add_u64 v[32:33], s[8:9], 0, v[88:89]
	v_lshlrev_b64 v[32:33], 12, v[32:33]
	v_lshl_add_u64 v[32:33], v[124:125], 0, v[32:33]
	global_load_dwordx4 v[134:137], v[32:33], off
	s_waitcnt vmcnt(0)
	s_branch .LBB0_255

; #define LAS __attribute__((address_space(3)))
; __device__ __forceinline__ void ret_mfma(const Params& P, LAS unsigned char* lds, int wave) {
;     ...
;         for (int c = 0; c < 64; ++c) {
; #pragma unroll
;             for (int i = 0; i < 4; ++i) { const int id = t + 512 * i, r = id >> 5, ch = id & 31;
;                 *(LAS u32x4*)(lds + Q_OFF + r * QP + ch * 16) = pq[i]; *(LAS u32x4*)(lds + K_OFF + r * QP + ch * 16) = pkk[i]; }
;             *(LAS u32x4*)(lds + V_OFF + vr * VP + vc * 16) = pvv;
;             __syncthreads();
.LBB0_255:
	s_add_i32 s14, s29, 1
	s_cmp_lg_u32 s29, 63
	s_waitcnt lgkmcnt(0)
	ds_write_b128 v173, v[48:51]
	ds_write_b128 v173, v[52:55] offset:33792
	ds_write_b128 v174, v[56:59]
	ds_write_b128 v174, v[60:63] offset:33792
	ds_write_b128 v175, v[64:67]
	ds_write_b128 v175, v[68:71] offset:33792
	ds_write_b128 v176, v[72:75]
	ds_write_b128 v176, v[76:79] offset:33792
	ds_write_b128 v177, v[80:83]
	s_waitcnt lgkmcnt(0)
	s_barrier
	s_andn2_b64 vcc, exec, s[10:11]
	s_cbranch_vccnz .Lret_wait_lo
	s_waitcnt vmcnt(5)
	s_branch .Lret_wait_done

; __device__ __forceinline__ void ret_mfma(const Params& P, LAS unsigned char* lds, int wave) {
;     ...
;             if (c + 1 < 64) { const size_t r1 = rb + (size_t)(c + 1) * 64;
; #pragma unroll
;                 for (int i = 0; i < 4; ++i) { const int id = t + 512 * i, r = id >> 5, ch = id & 31;
;                     pq[i] = *(const u32x4*)(QK + (r1 + r) * 2048 + hh * 256 + ch * 8); pkk[i] = *(const u32x4*)(QK + (r1 + r) * 2048 + 1024 + hh * 256 + ch * 8); }
;                 pvv = *(const u32x4*)(V + (r1 + vr) * 2048 + hh * 512 + slice * 64 + vc * 8); }
.Lret_wait_done:
	v_mov_b64_e32 v[48:49], v[226:227]
	v_mov_b64_e32 v[50:51], v[228:229]
	v_mov_b64_e32 v[52:53], v[230:231]
	v_mov_b64_e32 v[54:55], v[232:233]
	v_mov_b64_e32 v[56:57], v[234:235]
	v_mov_b64_e32 v[58:59], v[236:237]
	v_mov_b64_e32 v[60:61], v[238:239]
	v_mov_b64_e32 v[62:63], v[240:241]
	v_mov_b64_e32 v[64:65], v[246:247]
	v_mov_b64_e32 v[66:67], v[248:249]
	v_mov_b64_e32 v[68:69], v[250:251]
	v_mov_b64_e32 v[70:71], v[252:253]
	v_mov_b64_e32 v[72:73], v[206:207]
	v_mov_b64_e32 v[74:75], v[208:209]
	v_mov_b64_e32 v[76:77], v[130:131]
	v_mov_b64_e32 v[78:79], v[132:133]
	v_mov_b64_e32 v[80:81], v[134:135]
	v_mov_b64_e32 v[82:83], v[136:137]
	s_cmp_lt_u32 s29, 62
	s_cbranch_scc0 .LBB0_257
	s_lshl_b32 s8, s14, 6
	s_add_i32 s8, s8, 64
	s_add_u32 s8, s18, s8
	s_addc_u32 s9, s19, 0
	v_lshl_add_u64 v[32:33], s[8:9], 0, v[92:93]
	v_lshlrev_b64 v[32:33], 12, v[32:33]
	v_lshl_add_u64 v[32:33], v[144:145], 0, v[32:33]
	global_load_dwordx4 v[226:229], v[32:33], off
	global_load_dwordx4 v[230:233], v[32:33], off offset:2048
	v_lshl_add_u64 v[32:33], s[8:9], 0, v[94:95]
	v_lshlrev_b64 v[32:33], 12, v[32:33]
	v_lshl_add_u64 v[32:33], v[144:145], 0, v[32:33]
	global_load_dwordx4 v[234:237], v[32:33], off
	global_load_dwordx4 v[238:241], v[32:33], off offset:2048
	v_lshl_add_u64 v[32:33], s[8:9], 0, v[96:97]
	v_lshlrev_b64 v[32:33], 12, v[32:33]
	v_lshl_add_u64 v[32:33], v[144:145], 0, v[32:33]
	global_load_dwordx4 v[246:249], v[32:33], off
	global_load_dwordx4 v[250:253], v[32:33], off offset:2048
	v_lshl_add_u64 v[32:33], s[8:9], 0, v[98:99]
	v_lshlrev_b64 v[32:33], 12, v[32:33]
	v_lshl_add_u64 v[32:33], v[144:145], 0, v[32:33]
	global_load_dwordx4 v[206:209], v[32:33], off
	global_load_dwordx4 v[130:133], v[32:33], off offset:2048
	v_lshl_add_u64 v[32:33], s[8:9], 0, v[88:89]
	v_lshlrev_b64 v[32:33], 12, v[32:33]
	v_lshl_add_u64 v[32:33], v[124:125], 0, v[32:33]
	global_load_dwordx4 v[134:137], v[32:33], off
; #define LAS __attribute__((address_space(3)))
; __device__ __forceinline__ void ret_mfma(const Params& P, LAS unsigned char* lds, int wave) {
;     ...
;                 const int w4 = wave - 4, dvblk = w4 >> 1, nblk = w4 & 1, n = nblk * 32 + q32;
; #pragma unroll 4
;                 for (int ks = 0; ks < 16; ++ks) {
;                     const bf16x8 a = *(const LAS bf16x8*)(lds + ST_OFF + (dvblk * 32 + q32) * QP + ks * 32 + hf * 16);
;                     const bf16x8 bq = *(const LAS bf16x8*)(lds + Q_OFF + n * QP + ks * 32 + hf * 16);
;                     acc = __builtin_amdgcn_mfma_f32_32x32x16_bf16(a, bq, acc, 0, 0, 0);
;                 }
;                 acc = acc * dec[0];
;             }
;             __syncthreads();
;             {
; #pragma unroll
;                 for (int a = 0; a < 2; ++a) st[a] = st[a] * g64;
; #pragma unroll
;                 for (int ks = 0; ks < 4; ++ks) {
;                     bf16x8 av[2], bk;
; #pragma unroll
;                     for (int vb = 0; vb < 2; ++vb) { const LAS unsigned char* p = lds + V_OFF + (16 * ks + trrow) * VP + vb * 64 + trcol; av[vb] = tr_pair(p, p + 4 * VP); }
;                     { const LAS unsigned char* p = lds + K_OFF + (16 * ks + trrow) * QP + wave * 64 + trcol; bk = tr_pair(p, p + 4 * QP); }
; #pragma unroll
;                     for (int vb = 0; vb < 2; ++vb) st[vb] = __builtin_amdgcn_mfma_f32_32x32x16_bf16(av[vb], bk, st[vb], 0, 0, 0);
;                 }
.LBB0_257:
	v_add_u32_e32 v103, v148, v168
	ds_read_b64_tr_b16 v[190:191], v103
	ds_read_b64_tr_b16 v[192:193], v103 offset:768
	ds_read_b64_tr_b16 v[198:199], v179 offset:33792
	ds_read_b64_tr_b16 v[200:201], v179 offset:35904
	ds_read_b64_tr_b16 v[194:195], v103 offset:64
	ds_read_b64_tr_b16 v[196:197], v103 offset:832
	ds_read_b64_tr_b16 v[202:203], v103 offset:3072
	ds_read_b64_tr_b16 v[204:205], v103 offset:3840
	ds_read_b64_tr_b16 v[214:215], v179 offset:42240
	ds_read_b64_tr_b16 v[216:217], v179 offset:44352
	ds_read_b64_tr_b16 v[210:211], v103 offset:3136
	ds_read_b64_tr_b16 v[212:213], v103 offset:3904
	v_pk_mul_f32 v[0:1], v[126:127], v[0:1]
	v_pk_mul_f32 v[2:3], v[126:127], v[2:3]
	v_pk_mul_f32 v[4:5], v[126:127], v[4:5]
	v_pk_mul_f32 v[6:7], v[126:127], v[6:7]
	v_pk_mul_f32 v[8:9], v[126:127], v[8:9]
	v_pk_mul_f32 v[10:11], v[126:127], v[10:11]
	v_pk_mul_f32 v[12:13], v[126:127], v[12:13]
	v_pk_mul_f32 v[14:15], v[126:127], v[14:15]
	v_pk_mul_f32 v[16:17], v[126:127], v[16:17]
	v_pk_mul_f32 v[18:19], v[126:127], v[18:19]
	v_pk_mul_f32 v[20:21], v[126:127], v[20:21]
	v_pk_mul_f32 v[22:23], v[126:127], v[22:23]
	v_pk_mul_f32 v[24:25], v[126:127], v[24:25]
	v_pk_mul_f32 v[26:27], v[126:127], v[26:27]
	v_pk_mul_f32 v[28:29], v[126:127], v[28:29]
	v_pk_mul_f32 v[30:31], v[126:127], v[30:31]
	s_waitcnt lgkmcnt(6)
	v_mfma_f32_32x32x16_bf16 v[0:15], v[198:201], v[190:193], v[0:15]
	v_mfma_f32_32x32x16_bf16 v[16:31], v[198:201], v[194:197], v[16:31]
	ds_read_b64_tr_b16 v[190:191], v103 offset:6144
	ds_read_b64_tr_b16 v[192:193], v103 offset:6912
	ds_read_b64_tr_b16 v[198:199], v179 offset:50688
	ds_read_b64_tr_b16 v[200:201], v179 offset:52800
	ds_read_b64_tr_b16 v[194:195], v103 offset:6208
	ds_read_b64_tr_b16 v[196:197], v103 offset:6976
	s_waitcnt lgkmcnt(6)
	v_mfma_f32_32x32x16_bf16 v[0:15], v[214:217], v[202:205], v[0:15]
	v_mfma_f32_32x32x16_bf16 v[16:31], v[214:217], v[210:213], v[16:31]
	ds_read_b64_tr_b16 v[202:203], v103 offset:9216
	ds_read_b64_tr_b16 v[204:205], v103 offset:9984
	ds_read_b64_tr_b16 v[214:215], v179 offset:59136
	ds_read_b64_tr_b16 v[216:217], v179 offset:61248
	ds_read_b64_tr_b16 v[210:211], v103 offset:9280
	ds_read_b64_tr_b16 v[212:213], v103 offset:10048
	s_waitcnt lgkmcnt(6)
	v_mfma_f32_32x32x16_bf16 v[0:15], v[198:201], v[190:193], v[0:15]
	v_mfma_f32_32x32x16_bf16 v[16:31], v[198:201], v[194:197], v[16:31]
	s_waitcnt lgkmcnt(0)
	v_mfma_f32_32x32x16_bf16 v[0:15], v[214:217], v[202:205], v[0:15]
	v_mfma_f32_32x32x16_bf16 v[16:31], v[214:217], v[210:213], v[16:31]
	v_cndmask_b32_e64 v32, 0, 1, s[10:11]
	v_cmp_ne_u32_e64 s[8:9], 1, v32
	s_andn2_b64 vcc, exec, s[10:11]
	s_mov_b64 s[22:23], -1
	s_cbranch_vccnz .LBB0_261
	ds_read_b128 v[190:193], v171
	ds_read_b128 v[194:197], v150
	ds_read_b128 v[198:201], v171 offset:32
	ds_read_b128 v[202:205], v150 offset:32
	ds_read_b128 v[210:213], v171 offset:64
	ds_read_b128 v[214:217], v150 offset:64
	ds_read_b128 v[218:221], v171 offset:96
	ds_read_b128 v[222:225], v150 offset:96
	s_waitcnt lgkmcnt(6)
	v_mfma_f32_32x32x16_bf16 v[32:47], v[190:193], v[194:197], 0
	ds_read_b128 v[190:193], v171 offset:128
	ds_read_b128 v[194:197], v150 offset:128
	s_waitcnt lgkmcnt(6)
	v_mfma_f32_32x32x16_bf16 v[32:47], v[198:201], v[202:205], v[32:47]
	ds_read_b128 v[198:201], v171 offset:160
	ds_read_b128 v[202:205], v150 offset:160
	s_waitcnt lgkmcnt(6)
	v_mfma_f32_32x32x16_bf16 v[32:47], v[210:213], v[214:217], v[32:47]
	ds_read_b128 v[210:213], v171 offset:192
	ds_read_b128 v[214:217], v150 offset:192
	s_waitcnt lgkmcnt(6)
	v_mfma_f32_32x32x16_bf16 v[32:47], v[218:221], v[222:225], v[32:47]
	ds_read_b128 v[218:221], v171 offset:224
	ds_read_b128 v[222:225], v150 offset:224
	s_waitcnt lgkmcnt(6)
	v_mfma_f32_32x32x16_bf16 v[32:47], v[190:193], v[194:197], v[32:47]
	ds_read_b128 v[190:193], v171 offset:256
	ds_read_b128 v[194:197], v150 offset:256
	s_waitcnt lgkmcnt(6)
	v_mfma_f32_32x32x16_bf16 v[32:47], v[198:201], v[202:205], v[32:47]
	ds_read_b128 v[198:201], v171 offset:288
	ds_read_b128 v[202:205], v150 offset:288
	s_waitcnt lgkmcnt(6)
	v_mfma_f32_32x32x16_bf16 v[32:47], v[210:213], v[214:217], v[32:47]
	ds_read_b128 v[210:213], v171 offset:320
	ds_read_b128 v[214:217], v150 offset:320
	s_waitcnt lgkmcnt(6)
	v_mfma_f32_32x32x16_bf16 v[32:47], v[218:221], v[222:225], v[32:47]
	ds_read_b128 v[218:221], v171 offset:352
	ds_read_b128 v[222:225], v150 offset:352
	s_waitcnt lgkmcnt(6)
	v_mfma_f32_32x32x16_bf16 v[32:47], v[190:193], v[194:197], v[32:47]
	ds_read_b128 v[190:193], v171 offset:384
	ds_read_b128 v[194:197], v150 offset:384
	s_waitcnt lgkmcnt(6)
	v_mfma_f32_32x32x16_bf16 v[32:47], v[198:201], v[202:205], v[32:47]
	ds_read_b128 v[198:201], v171 offset:416
	ds_read_b128 v[202:205], v150 offset:416
	s_waitcnt lgkmcnt(6)
	v_mfma_f32_32x32x16_bf16 v[32:47], v[210:213], v[214:217], v[32:47]
	ds_read_b128 v[210:213], v171 offset:448
	ds_read_b128 v[214:217], v150 offset:448
	s_waitcnt lgkmcnt(6)
	v_mfma_f32_32x32x16_bf16 v[32:47], v[218:221], v[222:225], v[32:47]
	ds_read_b128 v[218:221], v171 offset:480
	ds_read_b128 v[222:225], v150 offset:480
	s_waitcnt lgkmcnt(6)
	v_mfma_f32_32x32x16_bf16 v[32:47], v[190:193], v[194:197], v[32:47]
	s_waitcnt lgkmcnt(4)
	v_mfma_f32_32x32x16_bf16 v[32:47], v[198:201], v[202:205], v[32:47]
	s_waitcnt lgkmcnt(2)
	v_mfma_f32_32x32x16_bf16 v[32:47], v[210:213], v[214:217], v[32:47]
	s_waitcnt lgkmcnt(0)
	v_mfma_f32_32x32x16_bf16 v[32:47], v[218:221], v[222:225], v[32:47]
	s_nop 11
	v_pk_mul_f32 v[46:47], v[108:109], v[46:47]
	v_pk_mul_f32 v[44:45], v[108:109], v[44:45]
	v_pk_mul_f32 v[42:43], v[108:109], v[42:43]
	v_pk_mul_f32 v[40:41], v[108:109], v[40:41]
	v_pk_mul_f32 v[38:39], v[108:109], v[38:39]
	v_pk_mul_f32 v[36:37], v[108:109], v[36:37]
	v_pk_mul_f32 v[34:35], v[108:109], v[34:35]
	v_pk_mul_f32 v[32:33], v[108:109], v[32:33]
	s_mov_b64 s[22:23], 0

; #define LAS __attribute__((address_space(3)))
; __device__ __forceinline__ unsigned cvt_pk_bf16(float lo, float hi) { f32x2 v = {lo, hi}; bf16x2_t b = __builtin_convertvector(v, bf16x2_t); return __builtin_bit_cast(unsigned, b); }
; __device__ __forceinline__ void ret_mfma(const Params& P, LAS unsigned char* lds, int wave) {
;     ...
; #pragma unroll
;                 for (int vb = 0; vb < 2; ++vb)
; #pragma unroll
;                     for (int i = 0; i < 16; ++i) { const int dv = vb * 32 + 8 * (i >> 2) + 4 * hf + (i & 3);
;                         *(LAS bf16_t*)(lds + ST_OFF + dv * QP + (wave * 32 + q32) * 2) = (bf16_t)(cvt_pk_bf16(st[vb][i], 0.f) & 0xffffu); }
;             }
;             if (wave >= 4) {
;                 const int w4 = wave - 4, dvblk = w4 >> 1, nblk = w4 & 1, n = nblk * 32 + q32;
; #pragma unroll
;                 for (int ks = 0; ks < 4; ++ks) {
;                     const LAS unsigned char* p = lds + V_OFF + (16 * ks + trrow) * VP + dvblk * 64 + trcol;
;                     const bf16x8 a = tr_pair(p, p + 4 * VP);
;                     const bf16x8 bs = *(const LAS bf16x8*)(lds + S_OFF + n * SP + (16 * ks + 8 * hf) * 2);
;                     acc = __builtin_amdgcn_mfma_f32_32x32x16_bf16(a, bs, acc, 0, 0, 0);
;                 }
;                 float sq = 0.f;
; #pragma unroll
;                 for (int i = 0; i < 16; ++i) sq += acc[i] * acc[i];
;                 sq += __shfl_xor(sq, 32);
;                 if (hf == 0) rssq[(r0 + n) * 64 + hh * 16 + slice * 2 + dvblk] = sq;
;                 bf16_t* op = V + (r0 + n) * 2048 + hh * 512 + slice * 64 + dvblk * 32 + 4 * hf;
; #pragma unroll
;                 for (int j = 0; j < 4; ++j) { u32x2 w; w.x = cvt_pk_bf16(acc[4 * j], acc[4 * j + 1]); w.y = cvt_pk_bf16(acc[4 * j + 2], acc[4 * j + 3]); *(u32x2*)(op + 8 * j) = w; }
.LBB0_265:
	s_waitcnt lgkmcnt(0)
	s_barrier
	s_and_b64 vcc, exec, s[8:9]
	v_cvt_pk_bf16_f32 v218, v0, v1
	v_cvt_pk_bf16_f32 v219, v2, v3
	ds_write_b64 v242, v[218:219]
	v_cvt_pk_bf16_f32 v220, v4, v5
	v_cvt_pk_bf16_f32 v221, v6, v7
	ds_write_b64 v242, v[220:221] offset:16
	v_cvt_pk_bf16_f32 v222, v8, v9
	v_cvt_pk_bf16_f32 v223, v10, v11
	ds_write_b64 v242, v[222:223] offset:32
	v_cvt_pk_bf16_f32 v224, v12, v13
	v_cvt_pk_bf16_f32 v225, v14, v15
	ds_write_b64 v242, v[224:225] offset:48
	v_cvt_pk_bf16_f32 v218, v16, v17
	v_cvt_pk_bf16_f32 v219, v18, v19
	ds_write_b64 v242, v[218:219] offset:16896
	v_cvt_pk_bf16_f32 v220, v20, v21
	v_cvt_pk_bf16_f32 v221, v22, v23
	ds_write_b64 v242, v[220:221] offset:16912
	v_cvt_pk_bf16_f32 v222, v24, v25
	v_cvt_pk_bf16_f32 v223, v26, v27
	ds_write_b64 v242, v[222:223] offset:16928
	v_cvt_pk_bf16_f32 v224, v28, v29
	v_cvt_pk_bf16_f32 v225, v30, v31
	ds_write_b64 v242, v[224:225] offset:16944
	s_cbranch_vccnz .LBB0_254
	ds_read_b64_tr_b16 v[190:191], v181
	ds_read_b64_tr_b16 v[192:193], v181 offset:768
	v_add_u32_e32 v103, v151, v149
	ds_read_b128 v[194:197], v103
	ds_read_b64_tr_b16 v[198:199], v181 offset:3072
	ds_read_b64_tr_b16 v[200:201], v181 offset:3840
	ds_read_b128 v[202:205], v103 offset:32
	v_and_b32_e32 v107, 64, v184
	v_add_u32_e32 v107, 64, v107
	s_waitcnt lgkmcnt(0)
	v_mfma_f32_32x32x16_bf16 v[32:47], v[190:193], v[194:197], v[32:47]
	s_lshl_b32 s8, s29, 6
	s_or_b32 s8, s18, s8
	v_or_b32_e32 v146, s8, v84
	v_mfma_f32_32x32x16_bf16 v[32:47], v[198:201], v[202:205], v[32:47]
	ds_read_b64_tr_b16 v[190:191], v181 offset:6144
	ds_read_b64_tr_b16 v[192:193], v181 offset:6912
	ds_read_b128 v[194:197], v103 offset:64
	ds_read_b64_tr_b16 v[198:199], v181 offset:9216
	ds_read_b64_tr_b16 v[200:201], v181 offset:9984
	ds_read_b128 v[202:205], v103 offset:96
	v_xor_b32_e32 v103, 32, v184
	v_cmp_lt_i32_e32 vcc, v103, v107
	s_nop 1
	v_cndmask_b32_e32 v107, v184, v103, vcc
	v_lshlrev_b32_e32 v107, 2, v107
	s_waitcnt lgkmcnt(0)
	v_mfma_f32_32x32x16_bf16 v[32:47], v[190:193], v[194:197], v[32:47]
	v_mfma_f32_32x32x16_bf16 v[32:47], v[198:201], v[202:205], v[32:47]
	s_nop 11
	v_mul_f32_e32 v103, v33, v33
	v_fmac_f32_e32 v103, v32, v32
	v_fmac_f32_e32 v103, v34, v34
	v_fmac_f32_e32 v103, v35, v35
	v_fmac_f32_e32 v103, v36, v36
	v_fmac_f32_e32 v103, v37, v37
	v_fmac_f32_e32 v103, v38, v38
	v_fmac_f32_e32 v103, v39, v39
	v_fmac_f32_e32 v103, v40, v40
	v_fmac_f32_e32 v103, v41, v41
	v_fmac_f32_e32 v103, v42, v42
	v_fmac_f32_e32 v103, v43, v43
	v_fmac_f32_e32 v103, v44, v44
	v_fmac_f32_e32 v103, v45, v45
	v_fmac_f32_e32 v103, v46, v46
	v_fmac_f32_e32 v103, v47, v47
	ds_bpermute_b32 v107, v107, v103
	s_and_saveexec_b64 s[8:9], s[6:7]
	s_xor_b64 s[8:9], exec, s[8:9]
	v_mov_b32_e32 v147, s19
	s_andn2_saveexec_b64 s[8:9], s[8:9]
	s_cbranch_execz .LBB0_253
	v_mov_b32_e32 v147, s19
	v_lshlrev_b64 v[190:191], 8, v[146:147]
	s_waitcnt lgkmcnt(0)
	v_add_f32_e32 v103, v103, v107
	v_lshl_add_u64 v[190:191], s[20:21], 0, v[190:191]
	flat_store_dword v[190:191], v103
	s_branch .LBB0_253
